# late prep tiles store write-through (sc0 sc1) and publish with a store drain only (no whole-L2 writeback per tile)
# speedup vs baseline: 1.0208x; 1.0113x over previous
.LBB0_549:
	s_or_b64 exec, exec, s[26:27]
	s_lshl_b32 s35, s34, 4
	v_mul_i32_i24_e32 v0, 0x1200, v29
	v_lshlrev_b32_e32 v9, 2, v6
	v_add_u32_e32 v8, s35, v29
	v_add3_u32 v0, 0, v0, v9
	v_cmp_lt_i32_e32 vcc, 63, v27
	ds_write_b128 v0, v[2:5]
	s_and_saveexec_b64 s[26:27], vcc
	s_xor_b64 s[26:27], exec, s[26:27]
	s_cbranch_execz .LBB0_553
	v_add_u32_e32 v0, 0xffffff60, v27
	v_cmp_gt_u32_e32 vcc, 64, v0
	s_and_saveexec_b64 s[42:43], vcc
	s_cbranch_execz .LBB0_552
	v_ashrrev_i32_e32 v9, 31, v8
	v_cvt_pk_bf16_f32 v2, v2, v3
	v_cvt_pk_bf16_f32 v3, v4, v5
	v_lshlrev_b64 v[4:5], 9, v[8:9]
	v_lshl_add_u64 v[4:5], s[92:93], 0, v[4:5]
	v_lshl_add_u64 v[4:5], v[6:7], 1, v[4:5]
	v_add_co_u32_e32 v4, vcc, 0x1267f000, v4
	s_nop 1
	v_addc_co_u32_e32 v5, vcc, 0, v5, vcc
	global_store_dwordx2 v[4:5], v[2:3], off offset:2816 sc0 sc1

.LBB0_553:
	s_andn2_saveexec_b64 s[26:27], s[26:27]
	s_cbranch_execz .LBB0_555
	v_ashrrev_i32_e32 v9, 31, v8
	v_readlane_b32 s2, v252, 8
	v_cvt_pk_bf16_f32 v2, v2, v3
	v_cvt_pk_bf16_f32 v3, v4, v5
	v_lshlrev_b64 v[4:5], 9, v[8:9]
	v_readlane_b32 s3, v252, 9
	s_nop 1
	v_lshl_add_u64 v[4:5], s[2:3], 0, v[4:5]
	v_lshl_add_u64 v[4:5], v[6:7], 1, v[4:5]
	global_store_dwordx2 v[4:5], v[2:3], off sc0 sc1

.LBB0_563:
	s_or_b64 exec, exec, s[26:27]
	v_mul_i32_i24_e32 v0, 0x1200, v31
	v_lshlrev_b32_e32 v11, 2, v8
	v_add_u32_e32 v10, s35, v31
	v_add3_u32 v0, 0, v0, v11
	v_cmp_lt_i32_e32 vcc, 63, v28
	ds_write_b128 v0, v[2:5]
	s_and_saveexec_b64 s[26:27], vcc
	s_xor_b64 s[26:27], exec, s[26:27]
	s_cbranch_execz .LBB0_567
	v_add_u32_e32 v0, 0xffffff60, v28
	v_cmp_gt_u32_e32 vcc, 64, v0
	s_and_saveexec_b64 s[42:43], vcc
	s_cbranch_execz .LBB0_566
	v_ashrrev_i32_e32 v11, 31, v10
	v_cvt_pk_bf16_f32 v2, v2, v3
	v_cvt_pk_bf16_f32 v3, v4, v5
	v_lshlrev_b64 v[4:5], 9, v[10:11]
	v_lshl_add_u64 v[4:5], s[92:93], 0, v[4:5]
	v_lshl_add_u64 v[4:5], v[8:9], 1, v[4:5]
	v_add_co_u32_e32 v4, vcc, 0x1267f000, v4
	s_nop 1
	v_addc_co_u32_e32 v5, vcc, 0, v5, vcc
	global_store_dwordx2 v[4:5], v[2:3], off offset:2816 sc0 sc1

.LBB0_567:
	s_andn2_saveexec_b64 s[26:27], s[26:27]
	s_cbranch_execz .LBB0_569
	v_ashrrev_i32_e32 v11, 31, v10
	v_readlane_b32 s2, v252, 8
	v_cvt_pk_bf16_f32 v2, v2, v3
	v_cvt_pk_bf16_f32 v3, v4, v5
	v_lshlrev_b64 v[4:5], 9, v[10:11]
	v_readlane_b32 s3, v252, 9
	s_nop 1
	v_lshl_add_u64 v[4:5], s[2:3], 0, v[4:5]
	v_lshl_add_u64 v[4:5], v[8:9], 1, v[4:5]
	global_store_dwordx2 v[4:5], v[2:3], off sc0 sc1

.LBB0_577:
	s_or_b64 exec, exec, s[26:27]
	v_mul_i32_i24_e32 v0, 0x1200, v33
	v_lshlrev_b32_e32 v13, 2, v10
	v_add_u32_e32 v12, s35, v33
	v_add3_u32 v0, 0, v0, v13
	v_cmp_lt_i32_e32 vcc, 63, v30
	ds_write_b128 v0, v[2:5]
	s_and_saveexec_b64 s[26:27], vcc
	s_xor_b64 s[26:27], exec, s[26:27]
	s_cbranch_execz .LBB0_581
	v_add_u32_e32 v0, 0xffffff60, v30
	v_cmp_gt_u32_e32 vcc, 64, v0
	s_and_saveexec_b64 s[42:43], vcc
	s_cbranch_execz .LBB0_580
	v_ashrrev_i32_e32 v13, 31, v12
	v_cvt_pk_bf16_f32 v2, v2, v3
	v_cvt_pk_bf16_f32 v3, v4, v5
	v_lshlrev_b64 v[4:5], 9, v[12:13]
	v_lshl_add_u64 v[4:5], s[92:93], 0, v[4:5]
	v_lshl_add_u64 v[4:5], v[10:11], 1, v[4:5]
	v_add_co_u32_e32 v4, vcc, 0x1267f000, v4
	s_nop 1
	v_addc_co_u32_e32 v5, vcc, 0, v5, vcc
	global_store_dwordx2 v[4:5], v[2:3], off offset:2816 sc0 sc1

.LBB0_581:
	s_andn2_saveexec_b64 s[26:27], s[26:27]
	s_cbranch_execz .LBB0_583
	v_ashrrev_i32_e32 v13, 31, v12
	v_readlane_b32 s2, v252, 8
	v_cvt_pk_bf16_f32 v2, v2, v3
	v_cvt_pk_bf16_f32 v3, v4, v5
	v_lshlrev_b64 v[4:5], 9, v[12:13]
	v_readlane_b32 s3, v252, 9
	s_nop 1
	v_lshl_add_u64 v[4:5], s[2:3], 0, v[4:5]
	v_lshl_add_u64 v[4:5], v[10:11], 1, v[4:5]
	global_store_dwordx2 v[4:5], v[2:3], off sc0 sc1

.LBB0_591:
	s_or_b64 exec, exec, s[26:27]
	v_mul_i32_i24_e32 v0, 0x1200, v35
	v_lshlrev_b32_e32 v15, 2, v12
	v_add_u32_e32 v14, s35, v35
	v_add3_u32 v0, 0, v0, v15
	v_cmp_lt_i32_e32 vcc, 63, v32
	ds_write_b128 v0, v[2:5]
	s_and_saveexec_b64 s[26:27], vcc
	s_xor_b64 s[26:27], exec, s[26:27]
	s_cbranch_execz .LBB0_595
	v_add_u32_e32 v0, 0xffffff60, v32
	v_cmp_gt_u32_e32 vcc, 64, v0
	s_and_saveexec_b64 s[42:43], vcc
	s_cbranch_execz .LBB0_594
	v_ashrrev_i32_e32 v15, 31, v14
	v_cvt_pk_bf16_f32 v2, v2, v3
	v_cvt_pk_bf16_f32 v3, v4, v5
	v_lshlrev_b64 v[4:5], 9, v[14:15]
	v_lshl_add_u64 v[4:5], s[92:93], 0, v[4:5]
	v_lshl_add_u64 v[4:5], v[12:13], 1, v[4:5]
	v_add_co_u32_e32 v4, vcc, 0x1267f000, v4
	s_nop 1
	v_addc_co_u32_e32 v5, vcc, 0, v5, vcc
	global_store_dwordx2 v[4:5], v[2:3], off offset:2816 sc0 sc1

.LBB0_595:
	s_andn2_saveexec_b64 s[26:27], s[26:27]
	s_cbranch_execz .LBB0_597
	v_ashrrev_i32_e32 v15, 31, v14
	v_readlane_b32 s2, v252, 8
	v_cvt_pk_bf16_f32 v2, v2, v3
	v_cvt_pk_bf16_f32 v3, v4, v5
	v_lshlrev_b64 v[4:5], 9, v[14:15]
	v_readlane_b32 s3, v252, 9
	s_nop 1
	v_lshl_add_u64 v[4:5], s[2:3], 0, v[4:5]
	v_lshl_add_u64 v[4:5], v[12:13], 1, v[4:5]
	global_store_dwordx2 v[4:5], v[2:3], off sc0 sc1

.LBB0_605:
	s_or_b64 exec, exec, s[26:27]
	v_mul_i32_i24_e32 v0, 0x1200, v37
	v_lshlrev_b32_e32 v17, 2, v14
	v_add_u32_e32 v16, s35, v37
	v_add3_u32 v0, 0, v0, v17
	v_cmp_lt_i32_e32 vcc, 63, v34
	ds_write_b128 v0, v[2:5]
	s_and_saveexec_b64 s[26:27], vcc
	s_xor_b64 s[26:27], exec, s[26:27]
	s_cbranch_execz .LBB0_609
	v_add_u32_e32 v0, 0xffffff60, v34
	v_cmp_gt_u32_e32 vcc, 64, v0
	s_and_saveexec_b64 s[42:43], vcc
	s_cbranch_execz .LBB0_608
	v_ashrrev_i32_e32 v17, 31, v16
	v_cvt_pk_bf16_f32 v2, v2, v3
	v_cvt_pk_bf16_f32 v3, v4, v5
	v_lshlrev_b64 v[4:5], 9, v[16:17]
	v_lshl_add_u64 v[4:5], s[92:93], 0, v[4:5]
	v_lshl_add_u64 v[4:5], v[14:15], 1, v[4:5]
	v_add_co_u32_e32 v4, vcc, 0x1267f000, v4
	s_nop 1
	v_addc_co_u32_e32 v5, vcc, 0, v5, vcc
	global_store_dwordx2 v[4:5], v[2:3], off offset:2816 sc0 sc1

.LBB0_609:
	s_andn2_saveexec_b64 s[26:27], s[26:27]
	s_cbranch_execz .LBB0_611
	v_ashrrev_i32_e32 v17, 31, v16
	v_readlane_b32 s2, v252, 8
	v_cvt_pk_bf16_f32 v2, v2, v3
	v_cvt_pk_bf16_f32 v3, v4, v5
	v_lshlrev_b64 v[4:5], 9, v[16:17]
	v_readlane_b32 s3, v252, 9
	s_nop 1
	v_lshl_add_u64 v[4:5], s[2:3], 0, v[4:5]
	v_lshl_add_u64 v[4:5], v[14:15], 1, v[4:5]
	global_store_dwordx2 v[4:5], v[2:3], off sc0 sc1

.LBB0_619:
	s_or_b64 exec, exec, s[26:27]
	v_mul_i32_i24_e32 v0, 0x1200, v39
	v_lshlrev_b32_e32 v19, 2, v16
	v_add_u32_e32 v18, s35, v39
	v_add3_u32 v0, 0, v0, v19
	v_cmp_lt_i32_e32 vcc, 63, v36
	ds_write_b128 v0, v[2:5]
	s_and_saveexec_b64 s[26:27], vcc
	s_xor_b64 s[26:27], exec, s[26:27]
	s_cbranch_execz .LBB0_623
	v_add_u32_e32 v0, 0xffffff60, v36
	v_cmp_gt_u32_e32 vcc, 64, v0
	s_and_saveexec_b64 s[42:43], vcc
	s_cbranch_execz .LBB0_622
	v_ashrrev_i32_e32 v19, 31, v18
	v_cvt_pk_bf16_f32 v2, v2, v3
	v_cvt_pk_bf16_f32 v3, v4, v5
	v_lshlrev_b64 v[4:5], 9, v[18:19]
	v_lshl_add_u64 v[4:5], s[92:93], 0, v[4:5]
	v_lshl_add_u64 v[4:5], v[16:17], 1, v[4:5]
	v_add_co_u32_e32 v4, vcc, 0x1267f000, v4
	s_nop 1
	v_addc_co_u32_e32 v5, vcc, 0, v5, vcc
	global_store_dwordx2 v[4:5], v[2:3], off offset:2816 sc0 sc1

.LBB0_623:
	s_andn2_saveexec_b64 s[26:27], s[26:27]
	s_cbranch_execz .LBB0_625
	v_ashrrev_i32_e32 v19, 31, v18
	v_readlane_b32 s2, v252, 8
	v_cvt_pk_bf16_f32 v2, v2, v3
	v_cvt_pk_bf16_f32 v3, v4, v5
	v_lshlrev_b64 v[4:5], 9, v[18:19]
	v_readlane_b32 s3, v252, 9
	s_nop 1
	v_lshl_add_u64 v[4:5], s[2:3], 0, v[4:5]
	v_lshl_add_u64 v[4:5], v[16:17], 1, v[4:5]
	global_store_dwordx2 v[4:5], v[2:3], off sc0 sc1

.LBB0_633:
	s_or_b64 exec, exec, s[26:27]
	v_mul_i32_i24_e32 v0, 0x1200, v41
	v_lshlrev_b32_e32 v21, 2, v18
	v_add_u32_e32 v20, s35, v41
	v_add3_u32 v0, 0, v0, v21
	v_cmp_lt_i32_e32 vcc, 63, v38
	ds_write_b128 v0, v[2:5]
	s_and_saveexec_b64 s[26:27], vcc
	s_xor_b64 s[26:27], exec, s[26:27]
	s_cbranch_execz .LBB0_637
	v_add_u32_e32 v0, 0xffffff60, v38
	v_cmp_gt_u32_e32 vcc, 64, v0
	s_and_saveexec_b64 s[42:43], vcc
	s_cbranch_execz .LBB0_636
	v_ashrrev_i32_e32 v21, 31, v20
	v_cvt_pk_bf16_f32 v2, v2, v3
	v_cvt_pk_bf16_f32 v3, v4, v5
	v_lshlrev_b64 v[4:5], 9, v[20:21]
	v_lshl_add_u64 v[4:5], s[92:93], 0, v[4:5]
	v_lshl_add_u64 v[4:5], v[18:19], 1, v[4:5]
	v_add_co_u32_e32 v4, vcc, 0x1267f000, v4
	s_nop 1
	v_addc_co_u32_e32 v5, vcc, 0, v5, vcc
	global_store_dwordx2 v[4:5], v[2:3], off offset:2816 sc0 sc1

.LBB0_637:
	s_andn2_saveexec_b64 s[26:27], s[26:27]
	s_cbranch_execz .LBB0_639
	v_ashrrev_i32_e32 v21, 31, v20
	v_readlane_b32 s2, v252, 8
	v_cvt_pk_bf16_f32 v2, v2, v3
	v_cvt_pk_bf16_f32 v3, v4, v5
	v_lshlrev_b64 v[4:5], 9, v[20:21]
	v_readlane_b32 s3, v252, 9
	s_nop 1
	v_lshl_add_u64 v[4:5], s[2:3], 0, v[4:5]
	v_lshl_add_u64 v[4:5], v[18:19], 1, v[4:5]
	global_store_dwordx2 v[4:5], v[2:3], off sc0 sc1

.LBB0_647:
	s_or_b64 exec, exec, s[26:27]
	v_mul_i32_i24_e32 v0, 0x1200, v43
	v_lshlrev_b32_e32 v23, 2, v20
	v_add_u32_e32 v22, s35, v43
	v_add3_u32 v0, 0, v0, v23
	v_cmp_lt_i32_e32 vcc, 63, v40
	ds_write_b128 v0, v[2:5]
	s_and_saveexec_b64 s[26:27], vcc
	s_xor_b64 s[26:27], exec, s[26:27]
	s_cbranch_execz .LBB0_651
	v_add_u32_e32 v0, 0xffffff60, v40
	v_cmp_gt_u32_e32 vcc, 64, v0
	s_and_saveexec_b64 s[42:43], vcc
	s_cbranch_execz .LBB0_650
	v_ashrrev_i32_e32 v23, 31, v22
	v_cvt_pk_bf16_f32 v2, v2, v3
	v_cvt_pk_bf16_f32 v3, v4, v5
	v_lshlrev_b64 v[4:5], 9, v[22:23]
	v_lshl_add_u64 v[4:5], s[92:93], 0, v[4:5]
	v_lshl_add_u64 v[4:5], v[20:21], 1, v[4:5]
	v_add_co_u32_e32 v4, vcc, 0x1267f000, v4
	s_nop 1
	v_addc_co_u32_e32 v5, vcc, 0, v5, vcc
	global_store_dwordx2 v[4:5], v[2:3], off offset:2816 sc0 sc1

.LBB0_651:
	s_andn2_saveexec_b64 s[26:27], s[26:27]
	s_cbranch_execz .LBB0_653
	v_ashrrev_i32_e32 v23, 31, v22
	v_readlane_b32 s2, v252, 8
	v_cvt_pk_bf16_f32 v2, v2, v3
	v_cvt_pk_bf16_f32 v3, v4, v5
	v_lshlrev_b64 v[4:5], 9, v[22:23]
	v_readlane_b32 s3, v252, 9
	s_nop 1
	v_lshl_add_u64 v[4:5], s[2:3], 0, v[4:5]
	v_lshl_add_u64 v[4:5], v[20:21], 1, v[4:5]
	global_store_dwordx2 v[4:5], v[2:3], off sc0 sc1

.LBB0_661:
	s_or_b64 exec, exec, s[26:27]
	v_mul_i32_i24_e32 v0, 0x1200, v45
	v_lshlrev_b32_e32 v25, 2, v22
	v_add_u32_e32 v24, s35, v45
	v_add3_u32 v0, 0, v0, v25
	v_cmp_lt_i32_e32 vcc, 63, v42
	ds_write_b128 v0, v[2:5]
	s_and_saveexec_b64 s[26:27], vcc
	s_xor_b64 s[26:27], exec, s[26:27]
	s_cbranch_execz .LBB0_665
	v_add_u32_e32 v0, 0xffffff60, v42
	v_cmp_gt_u32_e32 vcc, 64, v0
	s_and_saveexec_b64 s[42:43], vcc
	s_cbranch_execz .LBB0_664
	v_ashrrev_i32_e32 v25, 31, v24
	v_cvt_pk_bf16_f32 v2, v2, v3
	v_cvt_pk_bf16_f32 v3, v4, v5
	v_lshlrev_b64 v[4:5], 9, v[24:25]
	v_lshl_add_u64 v[4:5], s[92:93], 0, v[4:5]
	v_lshl_add_u64 v[4:5], v[22:23], 1, v[4:5]
	v_add_co_u32_e32 v4, vcc, 0x1267f000, v4
	s_nop 1
	v_addc_co_u32_e32 v5, vcc, 0, v5, vcc
	global_store_dwordx2 v[4:5], v[2:3], off offset:2816 sc0 sc1

.LBB0_665:
	s_andn2_saveexec_b64 s[26:27], s[26:27]
	s_cbranch_execz .LBB0_667
	v_ashrrev_i32_e32 v25, 31, v24
	v_readlane_b32 s2, v252, 8
	v_cvt_pk_bf16_f32 v2, v2, v3
	v_cvt_pk_bf16_f32 v3, v4, v5
	v_lshlrev_b64 v[4:5], 9, v[24:25]
	v_readlane_b32 s3, v252, 9
	s_nop 1
	v_lshl_add_u64 v[4:5], s[2:3], 0, v[4:5]
	v_lshl_add_u64 v[4:5], v[22:23], 1, v[4:5]
	global_store_dwordx2 v[4:5], v[2:3], off sc0 sc1
.LBB0_667:
	s_or_b64 exec, exec, s[26:27]
	v_and_b32_e32 v44, 63, v26
	v_readlane_b32 s2, v250, 60
	v_readlane_b32 s4, v251, 8
	v_readlane_b32 s10, v251, 14
	v_or_b32_e32 v2, s2, v44
	v_ashrrev_i32_e32 v3, 31, v2
	v_readlane_b32 s11, v251, 15
	s_waitcnt lgkmcnt(0)
	s_barrier
	v_lshl_add_u64 v[2:3], v[2:3], 2, s[10:11]
	v_mov_b32_e32 v47, v226
	v_ashrrev_i32_e32 v46, 5, v26
	v_and_b32_e32 v94, -2, v46
	s_movk_i32 s2, 0x1200
	v_lshlrev_b32_e32 v0, 2, v44
	v_mul_lo_u32 v4, v94, s2
	v_add3_u32 v48, 0, v4, v0
	ds_read_b32 v49, v48 offset:1536
	v_readlane_b32 s3, v250, 61
	v_readlane_b32 s2, v252, 20
	v_readlane_b32 s3, v252, 21
	s_ashr_i32 s35, s34, 31
	s_lshl_b64 s[34:35], s[34:35], 4
	v_lshl_add_u64 v[4:5], s[2:3], 0, v[0:1]
	v_ashrrev_i32_e32 v95, 31, v94
	v_lshl_add_u64 v[24:25], s[34:35], 0, v[94:95]
	v_lshlrev_b64 v[24:25], 10, v[24:25]
	v_cmp_eq_u32_e32 vcc, 0, v44
	v_lshl_add_u64 v[24:25], v[4:5], 0, v[24:25]
	v_readlane_b32 s5, v251, 9
	v_readlane_b32 s6, v251, 10
	v_readlane_b32 s7, v251, 11
	v_readlane_b32 s8, v251, 12
	v_readlane_b32 s9, v251, 13
	v_readlane_b32 s12, v251, 16
	v_readlane_b32 s13, v251, 17
	v_readlane_b32 s14, v251, 18
	v_readlane_b32 s15, v251, 19
	v_readlane_b32 s16, v251, 20
	v_readlane_b32 s17, v251, 21
	v_readlane_b32 s18, v251, 22
	v_readlane_b32 s19, v251, 23
	s_waitcnt lgkmcnt(0)
	v_mul_f32_e32 v52, v49, v47
	v_mul_f32_e32 v47, v52, v52
	s_nop 1
	v_mov_b32_dpp v47, v47 quad_perm:[1,0,3,2] row_mask:0xf bank_mask:0xf bound_ctrl:1
	v_fmac_f32_e32 v47, v52, v52
	s_nop 1
	v_add_f32_dpp v47, v47, v47 quad_perm:[2,3,0,1] row_mask:0xf bank_mask:0xf bound_ctrl:1
	s_nop 1
	v_add_f32_dpp v47, v47, v47 row_half_mirror row_mask:0xf bank_mask:0xf bound_ctrl:1
	s_nop 1
	v_add_f32_dpp v47, v47, v47 row_ror:8 row_mask:0xf bank_mask:0xf bound_ctrl:1
	s_nop 0
	v_readlane_b32 s2, v47, 16
	v_readlane_b32 s3, v47, 48
	v_readlane_b32 s26, v47, 0
	v_readlane_b32 s27, v47, 32
	v_mov_b32_e32 v50, s2
	v_mov_b32_e32 v51, s3
	v_pk_add_f32 v[50:51], s[26:27], v[50:51]
	s_nop 0
	v_add_f32_e32 v47, v50, v51
	v_rsq_f32_e32 v49, v47
	v_lshlrev_b32_e32 v47, 4, v94
	v_min_f32_e32 v49, 0x5368d4a5, v49
	v_mul_f32_e32 v50, v52, v49
	global_store_dword v[24:25], v50, off sc0 sc1
	s_and_saveexec_b64 s[26:27], vcc
	v_add_u32_e32 v50, 0, v47
	v_add_u32_e32 v50, 0x12000, v50
	ds_write_b32 v50, v49
	s_or_b64 exec, exec, s[26:27]
	v_mov_b32_e32 v49, v227
	ds_read_b32 v50, v48 offset:1792
	s_waitcnt lgkmcnt(0)
	v_mul_f32_e32 v52, v50, v49
	v_mul_f32_e32 v49, v52, v52
	s_nop 1
	v_mov_b32_dpp v49, v49 quad_perm:[1,0,3,2] row_mask:0xf bank_mask:0xf bound_ctrl:1
	v_fmac_f32_e32 v49, v52, v52
	s_nop 1
	v_add_f32_dpp v49, v49, v49 quad_perm:[2,3,0,1] row_mask:0xf bank_mask:0xf bound_ctrl:1
	s_nop 1
	v_add_f32_dpp v49, v49, v49 row_half_mirror row_mask:0xf bank_mask:0xf bound_ctrl:1
	s_nop 1
	v_add_f32_dpp v49, v49, v49 row_ror:8 row_mask:0xf bank_mask:0xf bound_ctrl:1
	s_nop 0
	v_readlane_b32 s2, v49, 16
	v_readlane_b32 s3, v49, 48
	v_readlane_b32 s26, v49, 0
	v_readlane_b32 s27, v49, 32
	v_mov_b32_e32 v50, s2
	v_mov_b32_e32 v51, s3
	v_pk_add_f32 v[50:51], s[26:27], v[50:51]
	s_nop 0
	v_add_f32_e32 v49, v50, v51
	v_rsq_f32_e32 v49, v49
	s_nop 0
	v_min_f32_e32 v49, 0x5368d4a5, v49
	v_mul_f32_e32 v50, v52, v49
	global_store_dword v[24:25], v50, off offset:256 sc0 sc1
	s_and_saveexec_b64 s[26:27], vcc
	s_add_i32 s2, 0, 0x12000
	v_add_u32_e32 v50, s2, v47
	ds_write_b32 v50, v49 offset:4
	s_or_b64 exec, exec, s[26:27]
	v_mov_b32_e32 v49, v228
	ds_read_b32 v50, v48 offset:2048
	s_waitcnt lgkmcnt(0)
	v_mul_f32_e32 v52, v50, v49
	v_mul_f32_e32 v49, v52, v52
	s_nop 1
	v_mov_b32_dpp v49, v49 quad_perm:[1,0,3,2] row_mask:0xf bank_mask:0xf bound_ctrl:1
	v_fmac_f32_e32 v49, v52, v52
	s_nop 1
	v_add_f32_dpp v49, v49, v49 quad_perm:[2,3,0,1] row_mask:0xf bank_mask:0xf bound_ctrl:1
	s_nop 1
	v_add_f32_dpp v49, v49, v49 row_half_mirror row_mask:0xf bank_mask:0xf bound_ctrl:1
	s_nop 1
	v_add_f32_dpp v49, v49, v49 row_ror:8 row_mask:0xf bank_mask:0xf bound_ctrl:1
	s_nop 0
	v_readlane_b32 s2, v49, 16
	v_readlane_b32 s3, v49, 48
	v_readlane_b32 s26, v49, 0
	v_readlane_b32 s27, v49, 32
	v_mov_b32_e32 v50, s2
	v_mov_b32_e32 v51, s3
	v_pk_add_f32 v[50:51], s[26:27], v[50:51]
	s_nop 0
	v_add_f32_e32 v49, v50, v51
	v_rsq_f32_e32 v49, v49
	s_nop 0
	v_min_f32_e32 v49, 0x5368d4a5, v49
	v_mul_f32_e32 v50, v52, v49
	global_store_dword v[24:25], v50, off offset:512 sc0 sc1
	s_and_saveexec_b64 s[26:27], vcc
	s_add_i32 s2, 0, 0x12000
	v_add_u32_e32 v50, s2, v47
	ds_write_b32 v50, v49 offset:8
	s_or_b64 exec, exec, s[26:27]
	v_mov_b32_e32 v49, v229
	ds_read_b32 v48, v48 offset:2304
	s_waitcnt lgkmcnt(0)
	v_mul_f32_e32 v50, v48, v49
	v_mul_f32_e32 v48, v50, v50
	s_nop 1
	v_mov_b32_dpp v48, v48 quad_perm:[1,0,3,2] row_mask:0xf bank_mask:0xf bound_ctrl:1
	v_fmac_f32_e32 v48, v50, v50
	s_nop 1
	v_add_f32_dpp v48, v48, v48 quad_perm:[2,3,0,1] row_mask:0xf bank_mask:0xf bound_ctrl:1
	s_nop 1
	v_add_f32_dpp v48, v48, v48 row_half_mirror row_mask:0xf bank_mask:0xf bound_ctrl:1
	s_nop 1
	v_add_f32_dpp v48, v48, v48 row_ror:8 row_mask:0xf bank_mask:0xf bound_ctrl:1
	s_nop 0
	v_readlane_b32 s2, v48, 16
	v_readlane_b32 s3, v48, 48
	v_readlane_b32 s26, v48, 0
	v_readlane_b32 s27, v48, 32
	v_mov_b32_e32 v48, s2
	v_mov_b32_e32 v49, s3
	v_pk_add_f32 v[48:49], s[26:27], v[48:49]
	s_nop 0
	v_add_f32_e32 v48, v48, v49
	v_rsq_f32_e32 v48, v48
	s_nop 0
	v_min_f32_e32 v48, 0x5368d4a5, v48
	v_mul_f32_e32 v49, v50, v48
	global_store_dword v[24:25], v49, off offset:768 sc0 sc1
	s_and_saveexec_b64 s[26:27], vcc
	s_add_i32 s2, 0, 0x12000
	v_add_u32_e32 v24, s2, v47
	ds_write_b32 v24, v48 offset:12
	s_or_b64 exec, exec, s[26:27]
	v_or_b32_e32 v46, 1, v46
	s_movk_i32 s2, 0x1200
	v_mul_lo_u32 v24, v46, s2
	v_ashrrev_i32_e32 v47, 31, v46
	v_add3_u32 v24, 0, v24, v0
	v_lshl_add_u64 v[48:49], s[34:35], 0, v[46:47]
	v_lshlrev_b32_e32 v0, 4, v46
	v_mov_b32_e32 v46, v226
	ds_read_b32 v25, v24 offset:1536
	v_lshlrev_b64 v[48:49], 10, v[48:49]
	v_lshl_add_u64 v[4:5], v[4:5], 0, v[48:49]
	s_waitcnt lgkmcnt(0)
	v_mul_f32_e32 v48, v25, v46
	v_mul_f32_e32 v25, v48, v48
	s_nop 1
	v_mov_b32_dpp v25, v25 quad_perm:[1,0,3,2] row_mask:0xf bank_mask:0xf bound_ctrl:1
	v_fmac_f32_e32 v25, v48, v48
	s_nop 1
	v_add_f32_dpp v25, v25, v25 quad_perm:[2,3,0,1] row_mask:0xf bank_mask:0xf bound_ctrl:1
	s_nop 1
	v_add_f32_dpp v25, v25, v25 row_half_mirror row_mask:0xf bank_mask:0xf bound_ctrl:1
	s_nop 1
	v_add_f32_dpp v25, v25, v25 row_ror:8 row_mask:0xf bank_mask:0xf bound_ctrl:1
	s_nop 0
	v_readlane_b32 s2, v25, 16
	v_readlane_b32 s3, v25, 48
	v_readlane_b32 s26, v25, 0
	v_readlane_b32 s27, v25, 32
	v_mov_b32_e32 v46, s2
	v_mov_b32_e32 v47, s3
	v_pk_add_f32 v[46:47], s[26:27], v[46:47]
	s_nop 0
	v_add_f32_e32 v25, v46, v47
	v_rsq_f32_e32 v25, v25
	s_nop 0
	v_min_f32_e32 v25, 0x5368d4a5, v25
	v_mul_f32_e32 v46, v48, v25
	global_store_dword v[4:5], v46, off sc0 sc1
	s_and_saveexec_b64 s[26:27], vcc
	v_add_u32_e32 v46, 0, v0
	v_add_u32_e32 v46, 0x12000, v46
	ds_write_b32 v46, v25
	s_or_b64 exec, exec, s[26:27]
	v_mov_b32_e32 v25, v227
	ds_read_b32 v46, v24 offset:1792
	s_waitcnt lgkmcnt(0)
	v_mul_f32_e32 v48, v46, v25
	v_mul_f32_e32 v25, v48, v48
	s_nop 1
	v_mov_b32_dpp v25, v25 quad_perm:[1,0,3,2] row_mask:0xf bank_mask:0xf bound_ctrl:1
	v_fmac_f32_e32 v25, v48, v48
	s_nop 1
	v_add_f32_dpp v25, v25, v25 quad_perm:[2,3,0,1] row_mask:0xf bank_mask:0xf bound_ctrl:1
	s_nop 1
	v_add_f32_dpp v25, v25, v25 row_half_mirror row_mask:0xf bank_mask:0xf bound_ctrl:1
	s_nop 1
	v_add_f32_dpp v25, v25, v25 row_ror:8 row_mask:0xf bank_mask:0xf bound_ctrl:1
	s_nop 0
	v_readlane_b32 s2, v25, 16
	v_readlane_b32 s3, v25, 48
	v_readlane_b32 s26, v25, 0
	v_readlane_b32 s27, v25, 32
	v_mov_b32_e32 v46, s2
	v_mov_b32_e32 v47, s3
	v_pk_add_f32 v[46:47], s[26:27], v[46:47]
	s_nop 0
	v_add_f32_e32 v25, v46, v47
	v_rsq_f32_e32 v25, v25
	s_nop 0
	v_min_f32_e32 v25, 0x5368d4a5, v25
	v_mul_f32_e32 v46, v48, v25
	global_store_dword v[4:5], v46, off offset:256 sc0 sc1
	s_and_saveexec_b64 s[26:27], vcc
	s_add_i32 s2, 0, 0x12000
	v_add_u32_e32 v46, s2, v0
	ds_write_b32 v46, v25 offset:4
	s_or_b64 exec, exec, s[26:27]
	v_mov_b32_e32 v25, v228
	ds_read_b32 v46, v24 offset:2048
	s_waitcnt lgkmcnt(0)
	v_mul_f32_e32 v48, v46, v25
	v_mul_f32_e32 v25, v48, v48
	s_nop 1
	v_mov_b32_dpp v25, v25 quad_perm:[1,0,3,2] row_mask:0xf bank_mask:0xf bound_ctrl:1
	v_fmac_f32_e32 v25, v48, v48
	s_nop 1
	v_add_f32_dpp v25, v25, v25 quad_perm:[2,3,0,1] row_mask:0xf bank_mask:0xf bound_ctrl:1
	s_nop 1
	v_add_f32_dpp v25, v25, v25 row_half_mirror row_mask:0xf bank_mask:0xf bound_ctrl:1
	s_nop 1
	v_add_f32_dpp v25, v25, v25 row_ror:8 row_mask:0xf bank_mask:0xf bound_ctrl:1
	s_nop 0
	v_readlane_b32 s2, v25, 16
	v_readlane_b32 s3, v25, 48
	v_readlane_b32 s26, v25, 0
	v_readlane_b32 s27, v25, 32
	v_mov_b32_e32 v46, s2
	v_mov_b32_e32 v47, s3
	v_pk_add_f32 v[46:47], s[26:27], v[46:47]
	s_nop 0
	v_add_f32_e32 v25, v46, v47
	v_rsq_f32_e32 v25, v25
	s_nop 0
	v_min_f32_e32 v25, 0x5368d4a5, v25
	v_mul_f32_e32 v46, v48, v25
	global_store_dword v[4:5], v46, off offset:512 sc0 sc1
	s_and_saveexec_b64 s[26:27], vcc
	s_add_i32 s2, 0, 0x12000
	v_add_u32_e32 v46, s2, v0
	ds_write_b32 v46, v25 offset:8
	s_or_b64 exec, exec, s[26:27]
	v_mov_b32_e32 v2, v229
	ds_read_b32 v3, v24 offset:2304
	s_waitcnt lgkmcnt(0)
	v_mul_f32_e32 v24, v3, v2
	v_mul_f32_e32 v2, v24, v24
	s_nop 1
	v_mov_b32_dpp v2, v2 quad_perm:[1,0,3,2] row_mask:0xf bank_mask:0xf bound_ctrl:1
	v_fmac_f32_e32 v2, v24, v24
	s_nop 1
	v_add_f32_dpp v2, v2, v2 quad_perm:[2,3,0,1] row_mask:0xf bank_mask:0xf bound_ctrl:1
	s_nop 1
	v_add_f32_dpp v2, v2, v2 row_half_mirror row_mask:0xf bank_mask:0xf bound_ctrl:1
	s_nop 1
	v_add_f32_dpp v2, v2, v2 row_ror:8 row_mask:0xf bank_mask:0xf bound_ctrl:1
	s_nop 0
	v_readlane_b32 s2, v2, 16
	v_readlane_b32 s3, v2, 48
	v_readlane_b32 s26, v2, 0
	v_readlane_b32 s27, v2, 32
	v_mov_b32_e32 v2, s2
	v_mov_b32_e32 v3, s3
	v_pk_add_f32 v[2:3], s[26:27], v[2:3]
	s_nop 0
	v_add_f32_e32 v2, v2, v3
	v_rsq_f32_e32 v2, v2
	s_nop 0
	v_min_f32_e32 v2, 0x5368d4a5, v2
	v_mul_f32_e32 v3, v24, v2
	global_store_dword v[4:5], v3, off offset:768 sc0 sc1
	s_and_saveexec_b64 s[26:27], vcc
	s_add_i32 s2, 0, 0x12000
	v_add_u32_e32 v0, s2, v0
	ds_write_b32 v0, v2 offset:12
	s_or_b64 exec, exec, s[26:27]
	s_cmp_lt_i32 s44, 0
	s_waitcnt lgkmcnt(0)
	s_barrier
	s_cbranch_scc1 .LBB0_935
	v_readlane_b32 s2, v252, 18
	v_readlane_b32 s3, v252, 19
	s_mov_b64 s[76:77], s[40:41]
	s_lshl_b32 s72, s44, 4
	s_mul_i32 s26, s72, 0x900
	s_add_u32 s42, s2, s26
	s_addc_u32 s43, s3, 0
	s_sub_u32 s46, s42, 0x24000
	s_subb_u32 s47, s43, 0
	s_movk_i32 s49, 0x900
	s_cmpk_lt_i32 s44, 0x400
	s_cbranch_scc0 .Lpi_ctx
	s_and_b32 s48, s72, 0xfff
	v_cmp_gt_u32_e32 vcc, 96, v27
	v_lshlrev_b32_e32 v0, 1, v27
	v_subrev_u32_e32 v2, 96, v27
	v_cndmask_b32_e32 v0, v2, v0, vcc
	v_mul_u32_u24_e32 v0, 0x556, v0
	v_lshrrev_b32_e32 v0, 16, v0
	v_and_b32_e32 v2, 1, v0
	v_lshl_add_u32 v2, v2, 1, -1
	v_lshrrev_b32_e32 v0, 1, v0
	v_mul_u32_u24_e32 v0, 6, v0
	v_lshlrev_b32_e32 v2, v0, v2
	v_lshlrev_b32_e64 v3, v0, 64
	v_add_u32_e32 v3, -1, v3
	v_mul_u32_u24_e32 v4, 0x480, v29
	v_add_lshl_u32 v4, v4, v6, 1
	global_load_dwordx2 v[58:59], v4, s[42:43]
	v_add_u32_e32 v5, 64, v2
	v_mad_u32_u24 v4, v5, s49, v4
	v_add_u32_e32 v5, s48, v29
	v_and_b32_e32 v5, v5, v3
	v_add_u32_e32 v5, v5, v2
	v_cmp_le_u32_e32 vcc, v5, v3
	v_mov_b32_e32 v60, 0
	v_mov_b32_e32 v61, 0
	s_and_saveexec_b64 s[26:27], vcc
	global_load_dwordx2 v[60:61], v4, s[46:47]
	s_mov_b64 exec, s[26:27]
	v_cmp_gt_u32_e32 vcc, 96, v28
	v_lshlrev_b32_e32 v0, 1, v28
	v_subrev_u32_e32 v2, 96, v28
	v_cndmask_b32_e32 v0, v2, v0, vcc
	v_mul_u32_u24_e32 v0, 0x556, v0
	v_lshrrev_b32_e32 v0, 16, v0
	v_and_b32_e32 v2, 1, v0
	v_lshl_add_u32 v2, v2, 1, -1
	v_lshrrev_b32_e32 v0, 1, v0
	v_mul_u32_u24_e32 v0, 6, v0
	v_lshlrev_b32_e32 v2, v0, v2
	v_lshlrev_b32_e64 v3, v0, 64
	v_add_u32_e32 v3, -1, v3
	v_mul_u32_u24_e32 v4, 0x480, v31
	v_add_lshl_u32 v4, v4, v8, 1
	global_load_dwordx2 v[62:63], v4, s[42:43]
	v_add_u32_e32 v5, 64, v2
	v_mad_u32_u24 v4, v5, s49, v4
	v_add_u32_e32 v5, s48, v31
	v_and_b32_e32 v5, v5, v3
	v_add_u32_e32 v5, v5, v2
	v_cmp_le_u32_e32 vcc, v5, v3
	v_mov_b32_e32 v64, 0
	v_mov_b32_e32 v65, 0
	s_and_saveexec_b64 s[26:27], vcc
	global_load_dwordx2 v[64:65], v4, s[46:47]
	s_mov_b64 exec, s[26:27]
	v_cmp_gt_u32_e32 vcc, 96, v30
	v_lshlrev_b32_e32 v0, 1, v30
	v_subrev_u32_e32 v2, 96, v30
	v_cndmask_b32_e32 v0, v2, v0, vcc
	v_mul_u32_u24_e32 v0, 0x556, v0
	v_lshrrev_b32_e32 v0, 16, v0
	v_and_b32_e32 v2, 1, v0
	v_lshl_add_u32 v2, v2, 1, -1
	v_lshrrev_b32_e32 v0, 1, v0
	v_mul_u32_u24_e32 v0, 6, v0
	v_lshlrev_b32_e32 v2, v0, v2
	v_lshlrev_b32_e64 v3, v0, 64
	v_add_u32_e32 v3, -1, v3
	v_mul_u32_u24_e32 v4, 0x480, v33
	v_add_lshl_u32 v4, v4, v10, 1
	global_load_dwordx2 v[66:67], v4, s[42:43]
	v_add_u32_e32 v5, 64, v2
	v_mad_u32_u24 v4, v5, s49, v4
	v_add_u32_e32 v5, s48, v33
	v_and_b32_e32 v5, v5, v3
	v_add_u32_e32 v5, v5, v2
	v_cmp_le_u32_e32 vcc, v5, v3
	v_mov_b32_e32 v68, 0
	v_mov_b32_e32 v69, 0
	s_and_saveexec_b64 s[26:27], vcc
	global_load_dwordx2 v[68:69], v4, s[46:47]
	s_mov_b64 exec, s[26:27]
	v_cmp_gt_u32_e32 vcc, 96, v32
	v_lshlrev_b32_e32 v0, 1, v32
	v_subrev_u32_e32 v2, 96, v32
	v_cndmask_b32_e32 v0, v2, v0, vcc
	v_mul_u32_u24_e32 v0, 0x556, v0
	v_lshrrev_b32_e32 v0, 16, v0
	v_and_b32_e32 v2, 1, v0
	v_lshl_add_u32 v2, v2, 1, -1
	v_lshrrev_b32_e32 v0, 1, v0
	v_mul_u32_u24_e32 v0, 6, v0
	v_lshlrev_b32_e32 v2, v0, v2
	v_lshlrev_b32_e64 v3, v0, 64
	v_add_u32_e32 v3, -1, v3
	v_mul_u32_u24_e32 v4, 0x480, v35
	v_add_lshl_u32 v4, v4, v12, 1
	global_load_dwordx2 v[70:71], v4, s[42:43]
	v_add_u32_e32 v5, 64, v2
	v_mad_u32_u24 v4, v5, s49, v4
	v_add_u32_e32 v5, s48, v35
	v_and_b32_e32 v5, v5, v3
	v_add_u32_e32 v5, v5, v2
	v_cmp_le_u32_e32 vcc, v5, v3
	v_mov_b32_e32 v72, 0
	v_mov_b32_e32 v73, 0
	s_and_saveexec_b64 s[26:27], vcc
	global_load_dwordx2 v[72:73], v4, s[46:47]
	s_mov_b64 exec, s[26:27]
	v_cmp_gt_u32_e32 vcc, 96, v34
	v_lshlrev_b32_e32 v0, 1, v34
	v_subrev_u32_e32 v2, 96, v34
	v_cndmask_b32_e32 v0, v2, v0, vcc
	v_mul_u32_u24_e32 v0, 0x556, v0
	v_lshrrev_b32_e32 v0, 16, v0
	v_and_b32_e32 v2, 1, v0
	v_lshl_add_u32 v2, v2, 1, -1
	v_lshrrev_b32_e32 v0, 1, v0
	v_mul_u32_u24_e32 v0, 6, v0
	v_lshlrev_b32_e32 v2, v0, v2
	v_lshlrev_b32_e64 v3, v0, 64
	v_add_u32_e32 v3, -1, v3
	v_mul_u32_u24_e32 v4, 0x480, v37
	v_add_lshl_u32 v4, v4, v14, 1
	global_load_dwordx2 v[74:75], v4, s[42:43]
	v_add_u32_e32 v5, 64, v2
	v_mad_u32_u24 v4, v5, s49, v4
	v_add_u32_e32 v5, s48, v37
	v_and_b32_e32 v5, v5, v3
	v_add_u32_e32 v5, v5, v2
	v_cmp_le_u32_e32 vcc, v5, v3
	v_mov_b32_e32 v76, 0
	v_mov_b32_e32 v77, 0
	s_and_saveexec_b64 s[26:27], vcc
	global_load_dwordx2 v[76:77], v4, s[46:47]
	s_mov_b64 exec, s[26:27]
	v_cmp_gt_u32_e32 vcc, 96, v36
	v_lshlrev_b32_e32 v0, 1, v36
	v_subrev_u32_e32 v2, 96, v36
	v_cndmask_b32_e32 v0, v2, v0, vcc
	v_mul_u32_u24_e32 v0, 0x556, v0
	v_lshrrev_b32_e32 v0, 16, v0
	v_and_b32_e32 v2, 1, v0
	v_lshl_add_u32 v2, v2, 1, -1
	v_lshrrev_b32_e32 v0, 1, v0
	v_mul_u32_u24_e32 v0, 6, v0
	v_lshlrev_b32_e32 v2, v0, v2
	v_lshlrev_b32_e64 v3, v0, 64
	v_add_u32_e32 v3, -1, v3
	v_mul_u32_u24_e32 v4, 0x480, v39
	v_add_lshl_u32 v4, v4, v16, 1
	global_load_dwordx2 v[78:79], v4, s[42:43]
	v_add_u32_e32 v5, 64, v2
	v_mad_u32_u24 v4, v5, s49, v4
	v_add_u32_e32 v5, s48, v39
	v_and_b32_e32 v5, v5, v3
	v_add_u32_e32 v5, v5, v2
	v_cmp_le_u32_e32 vcc, v5, v3
	v_mov_b32_e32 v80, 0
	v_mov_b32_e32 v81, 0
	s_and_saveexec_b64 s[26:27], vcc
	global_load_dwordx2 v[80:81], v4, s[46:47]
	s_mov_b64 exec, s[26:27]
	v_cmp_gt_u32_e32 vcc, 96, v38
	v_lshlrev_b32_e32 v0, 1, v38
	v_subrev_u32_e32 v2, 96, v38
	v_cndmask_b32_e32 v0, v2, v0, vcc
	v_mul_u32_u24_e32 v0, 0x556, v0
	v_lshrrev_b32_e32 v0, 16, v0
	v_and_b32_e32 v2, 1, v0
	v_lshl_add_u32 v2, v2, 1, -1
	v_lshrrev_b32_e32 v0, 1, v0
	v_mul_u32_u24_e32 v0, 6, v0
	v_lshlrev_b32_e32 v2, v0, v2
	v_lshlrev_b32_e64 v3, v0, 64
	v_add_u32_e32 v3, -1, v3
	v_mul_u32_u24_e32 v4, 0x480, v41
	v_add_lshl_u32 v4, v4, v18, 1
	global_load_dwordx2 v[82:83], v4, s[42:43]
	v_add_u32_e32 v5, 64, v2
	v_mad_u32_u24 v4, v5, s49, v4
	v_add_u32_e32 v5, s48, v41
	v_and_b32_e32 v5, v5, v3
	v_add_u32_e32 v5, v5, v2
	v_cmp_le_u32_e32 vcc, v5, v3
	v_mov_b32_e32 v84, 0
	v_mov_b32_e32 v85, 0
	s_and_saveexec_b64 s[26:27], vcc
	global_load_dwordx2 v[84:85], v4, s[46:47]
	s_mov_b64 exec, s[26:27]
	v_cmp_gt_u32_e32 vcc, 96, v40
	v_lshlrev_b32_e32 v0, 1, v40
	v_subrev_u32_e32 v2, 96, v40
	v_cndmask_b32_e32 v0, v2, v0, vcc
	v_mul_u32_u24_e32 v0, 0x556, v0
	v_lshrrev_b32_e32 v0, 16, v0
	v_and_b32_e32 v2, 1, v0
	v_lshl_add_u32 v2, v2, 1, -1
	v_lshrrev_b32_e32 v0, 1, v0
	v_mul_u32_u24_e32 v0, 6, v0
	v_lshlrev_b32_e32 v2, v0, v2
	v_lshlrev_b32_e64 v3, v0, 64
	v_add_u32_e32 v3, -1, v3
	v_mul_u32_u24_e32 v4, 0x480, v43
	v_add_lshl_u32 v4, v4, v20, 1
	global_load_dwordx2 v[86:87], v4, s[42:43]
	v_add_u32_e32 v5, 64, v2
	v_mad_u32_u24 v4, v5, s49, v4
	v_add_u32_e32 v5, s48, v43
	v_and_b32_e32 v5, v5, v3
	v_add_u32_e32 v5, v5, v2
	v_cmp_le_u32_e32 vcc, v5, v3
	v_mov_b32_e32 v88, 0
	v_mov_b32_e32 v89, 0
	s_and_saveexec_b64 s[26:27], vcc
	global_load_dwordx2 v[88:89], v4, s[46:47]
	s_mov_b64 exec, s[26:27]
	v_cmp_gt_u32_e32 vcc, 96, v42
	v_lshlrev_b32_e32 v0, 1, v42
	v_subrev_u32_e32 v2, 96, v42
	v_cndmask_b32_e32 v0, v2, v0, vcc
	v_mul_u32_u24_e32 v0, 0x556, v0
	v_lshrrev_b32_e32 v0, 16, v0
	v_and_b32_e32 v2, 1, v0
	v_lshl_add_u32 v2, v2, 1, -1
	v_lshrrev_b32_e32 v0, 1, v0
	v_mul_u32_u24_e32 v0, 6, v0
	v_lshlrev_b32_e32 v2, v0, v2
	v_lshlrev_b32_e64 v3, v0, 64
	v_add_u32_e32 v3, -1, v3
	v_mul_u32_u24_e32 v4, 0x480, v45
	v_add_lshl_u32 v4, v4, v22, 1
	global_load_dwordx2 v[90:91], v4, s[42:43]
	v_add_u32_e32 v5, 64, v2
	v_mad_u32_u24 v4, v5, s49, v4
	v_add_u32_e32 v5, s48, v45
	v_and_b32_e32 v5, v5, v3
	v_add_u32_e32 v5, v5, v2
	v_cmp_le_u32_e32 vcc, v5, v3
	v_mov_b32_e32 v92, 0
	v_mov_b32_e32 v93, 0
	s_and_saveexec_b64 s[26:27], vcc
	global_load_dwordx2 v[92:93], v4, s[46:47]
	s_mov_b64 exec, s[26:27]
	s_branch .Lpi_done

.LBB0_936:
	v_or_b32_e32 v0, s26, v94
	v_lshlrev_b32_e32 v114, 2, v0
	v_lshl_or_b32 v146, v0, 4, v95
	v_ashrrev_i32_e32 v115, 31, v114
	v_ashrrev_i32_e32 v147, 31, v146
	v_lshlrev_b64 v[114:115], 10, v[114:115]
	v_lshlrev_b64 v[188:189], 2, v[146:147]
	v_lshl_add_u64 v[114:115], v[96:97], 0, v[114:115]
	v_lshl_add_u64 v[54:55], s[86:87], 0, v[188:189]
	v_add_co_u32_e32 v126, vcc, s3, v114
	v_lshl_add_u32 v50, v146, 2, v108
	global_load_dwordx4 v[110:113], v[54:55], off
	v_lshl_add_u64 v[54:55], s[84:85], 0, v[188:189]
	v_addc_co_u32_e32 v127, vcc, 0, v115, vcc
	ds_read_b128 v[50:53], v50 offset:1536
	global_load_dwordx4 v[54:57], v[54:55], off
	s_nop 0
	global_load_dwordx4 v[114:117], v[126:127], off
	global_load_dwordx4 v[118:121], v[126:127], off offset:1024
	global_load_dwordx4 v[122:125], v[126:127], off offset:2048
	s_nop 0
	global_load_dwordx4 v[126:129], v[126:127], off offset:3072
	v_lshlrev_b32_e32 v172, 1, v0
	v_ashrrev_i32_e32 v173, 31, v172
	v_lshlrev_b64 v[130:131], 10, v[172:173]
	v_lshl_add_u64 v[168:169], v[96:97], 0, v[130:131]
	global_load_dwordx4 v[130:133], v[168:169], off
	v_or_b32_e32 v138, 1, v172
	v_ashrrev_i32_e32 v139, 31, v138
	v_add_co_u32_e32 v142, vcc, s20, v168
	v_lshlrev_b64 v[138:139], 10, v[138:139]
	s_nop 0
	v_addc_co_u32_e32 v143, vcc, 0, v169, vcc
	v_lshl_add_u64 v[138:139], v[96:97], 0, v[138:139]
	global_load_dwordx4 v[134:137], v[142:143], off
	s_nop 0
	global_load_dwordx4 v[138:141], v[138:139], off
	s_nop 0
	global_load_dwordx4 v[142:145], v[142:143], off offset:1024
	v_lshl_add_u64 v[180:181], s[88:89], 0, v[188:189]
	global_load_dwordx4 v[156:159], v[180:181], off
	v_lshl_add_u64 v[184:185], s[0:1], 0, v[188:189]
	global_load_dwordx4 v[160:163], v[184:185], off
	v_add_co_u32_e32 v164, vcc, s22, v168
	v_add_u32_e32 v172, 33, v172
	s_nop 0
	v_addc_co_u32_e32 v165, vcc, 0, v169, vcc
	v_ashrrev_i32_e32 v173, 31, v172
	v_add_co_u32_e32 v176, vcc, s2, v168
	v_lshlrev_b64 v[172:173], 10, v[172:173]
	s_nop 0
	v_addc_co_u32_e32 v177, vcc, 0, v169, vcc
	v_lshl_add_u64 v[172:173], v[96:97], 0, v[172:173]
	global_load_dwordx4 v[164:167], v[164:165], off
	s_mov_b32 s26, 1
	global_load_dwordx4 v[168:171], v[176:177], off
	s_nop 0
	global_load_dwordx4 v[172:175], v[172:173], off
	s_nop 0
	global_load_dwordx4 v[176:179], v[176:177], off offset:1024
	s_nop 0
	global_load_dwordx4 v[180:183], v[180:181], off offset:1024
	s_nop 0
	global_load_dwordx4 v[184:187], v[184:185], off offset:1024
	s_and_b64 vcc, exec, s[34:35]
	s_mov_b64 s[34:35], 0
	s_waitcnt vmcnt(15)
	v_mfma_f32_16x16x32_bf16 v[114:117], v[114:117], v[2:5], 0
	s_waitcnt lgkmcnt(0)
	v_pk_mul_f32 v[110:111], v[50:51], v[110:111]
	v_pk_mul_f32 v[112:113], v[52:53], v[112:113]
	s_waitcnt vmcnt(14)
	v_mfma_f32_16x16x32_bf16 v[114:117], v[118:121], v[6:9], v[114:117]
	s_waitcnt vmcnt(13)
	v_mfma_f32_16x16x32_bf16 v[114:117], v[122:125], v[10:13], v[114:117]
	v_lshlrev_b64 v[122:123], 1, v[146:147]
	v_pk_mul_f32 v[124:125], v[110:111], v[100:101]
	s_waitcnt vmcnt(12)
	v_mfma_f32_16x16x32_bf16 v[114:117], v[126:129], v[14:17], v[114:117]
	v_mul_f32_e64 v128, v112, v100
	v_mul_f32_e64 v129, v113, v101
	s_waitcnt vmcnt(10)
	v_mfma_f32_16x16x32_bf16 v[118:121], v[134:137], v[22:25], 0
	s_nop 3
	v_cvt_pk_bf16_f32 v114, v114, v115
	v_cvt_pk_bf16_f32 v115, v116, v117
	v_lshl_add_u64 v[116:117], v[98:99], 0, v[122:123]
	global_store_dwordx2 v[116:117], v[114:115], off sc0 sc1
	v_mfma_f32_16x16x32_bf16 v[114:117], v[130:133], v[18:21], 0
	v_lshl_add_u64 v[130:131], v[104:105], 0, v[188:189]
	s_waitcnt vmcnt(10)
	v_mfma_f32_16x16x32_bf16 v[114:117], v[138:141], v[26:29], v[114:117]
	s_waitcnt vmcnt(9)
	v_mfma_f32_16x16x32_bf16 v[118:121], v[142:145], v[30:33], v[118:121]
	s_waitcnt vmcnt(8)
	s_nop 4
	v_add_f32_e32 v0, v156, v114
	v_mul_f32_e32 v0, 0xbfb8aa3b, v0
	v_exp_f32_e32 v0, v0
	s_nop 0
	v_add_f32_e32 v0, 1.0, v0
	v_rcp_f32_e32 v0, v0
	s_nop 0
	v_mul_f32_e32 v0, 0xbf1b4598, v0
	v_mul_f32_e32 v0, 0x3fb8aa3b, v0
	v_exp_f32_e32 v114, v0
	s_waitcnt vmcnt(7)
	v_add_f32_e32 v0, v160, v118
	v_mul_f32_e32 v0, 0xbfb8aa3b, v0
	v_exp_f32_e32 v0, v0
	s_nop 0
	v_add_f32_e32 v0, 1.0, v0
	v_rcp_f32_e32 v118, v0
	v_add_f32_e32 v0, v157, v115
	v_mul_f32_e32 v0, 0xbfb8aa3b, v0
	v_exp_f32_e32 v0, v0
	s_nop 0
	v_add_f32_e32 v0, 1.0, v0
	v_rcp_f32_e32 v0, v0
	s_nop 0
	v_mul_f32_e32 v0, 0xbf1b4598, v0
	v_mul_f32_e32 v0, 0x3fb8aa3b, v0
	v_exp_f32_e32 v115, v0
	v_add_f32_e32 v0, v161, v119
	v_mul_f32_e32 v0, 0xbfb8aa3b, v0
	v_exp_f32_e32 v0, v0
	s_nop 0
	v_add_f32_e32 v0, 1.0, v0
	v_rcp_f32_e32 v119, v0
	v_add_f32_e32 v0, v158, v116
	v_mul_f32_e32 v0, 0xbfb8aa3b, v0
	v_exp_f32_e32 v0, v0
	v_pk_add_f32 v[110:111], v[118:119], -1.0 op_sel_hi:[1,0]
	v_add_f32_e32 v0, 1.0, v0
	v_rcp_f32_e32 v0, v0
	v_pk_fma_f32 v[110:111], v[54:55], v[110:111], 1.0 op_sel_hi:[1,1,0]
	v_mul_f32_e32 v0, 0xbf1b4598, v0
	v_mul_f32_e32 v0, 0x3fb8aa3b, v0
	v_exp_f32_e32 v116, v0
	v_add_f32_e32 v0, v162, v120
	v_mul_f32_e32 v0, 0xbfb8aa3b, v0
	v_exp_f32_e32 v0, v0
	v_pk_mul_f32 v[126:127], v[50:51], v[110:111]
	v_pk_mul_f32 v[110:111], v[124:125], v[118:119]
	v_add_f32_e32 v0, 1.0, v0
	v_rcp_f32_e32 v120, v0
	v_add_f32_e32 v0, v159, v117
	v_mul_f32_e32 v0, 0xbfb8aa3b, v0
	v_exp_f32_e32 v0, v0
	s_nop 0
	v_add_f32_e32 v0, 1.0, v0
	v_rcp_f32_e32 v0, v0
	s_nop 0
	v_mul_f32_e32 v0, 0xbf1b4598, v0
	v_mul_f32_e32 v0, 0x3fb8aa3b, v0
	v_exp_f32_e32 v117, v0
	v_add_f32_e32 v0, v163, v121
	v_mul_f32_e32 v0, 0xbfb8aa3b, v0
	v_exp_f32_e32 v0, v0
	s_nop 0
	v_add_f32_e32 v0, 1.0, v0
	v_rcp_f32_e32 v121, v0
	s_nop 0
	v_pk_add_f32 v[118:119], v[120:121], -1.0 op_sel_hi:[1,0]
	s_nop 0
	v_pk_fma_f32 v[118:119], v[56:57], v[118:119], 1.0 op_sel_hi:[1,1,0]
	v_pk_mul_f32 v[112:113], v[128:129], v[120:121]
	v_pk_mul_f32 v[118:119], v[52:53], v[118:119]
	v_lshl_add_u64 v[120:121], v[102:103], 0, v[188:189]
	global_store_dwordx4 v[130:131], v[110:113], off sc0 sc1
	global_store_dwordx4 v[120:121], v[114:117], off sc0 sc1
	s_nop 0
	v_cvt_pk_bf16_f32 v110, v126, v127
	v_cvt_pk_bf16_f32 v111, v118, v119
	v_lshl_add_u64 v[118:119], v[106:107], 0, v[122:123]
	global_store_dwordx2 v[118:119], v[110:111], off sc0 sc1
	s_waitcnt vmcnt(9)
	v_mfma_f32_16x16x32_bf16 v[110:113], v[164:167], v[34:37], 0
	s_waitcnt vmcnt(7)
	v_mfma_f32_16x16x32_bf16 v[110:113], v[172:175], v[42:45], v[110:113]
	v_mfma_f32_16x16x32_bf16 v[114:117], v[168:171], v[38:41], 0
	s_waitcnt vmcnt(6)
	v_mfma_f32_16x16x32_bf16 v[114:117], v[176:179], v[46:49], v[114:117]
	s_waitcnt vmcnt(5)
	s_nop 3
	v_add_f32_e32 v0, v180, v110
	v_mul_f32_e32 v0, 0xbfb8aa3b, v0
	v_exp_f32_e32 v0, v0
	s_nop 0
	v_add_f32_e32 v0, 1.0, v0
	v_rcp_f32_e32 v0, v0
	s_nop 0
	v_mul_f32_e32 v0, 0xbf1b4598, v0
	v_mul_f32_e32 v0, 0x3fb8aa3b, v0
	v_exp_f32_e32 v110, v0
	s_waitcnt vmcnt(4)
	v_add_f32_e32 v0, v184, v114
	v_mul_f32_e32 v0, 0xbfb8aa3b, v0
	v_exp_f32_e32 v0, v0
	s_nop 0
	v_add_f32_e32 v0, 1.0, v0
	v_rcp_f32_e32 v114, v0
	v_add_f32_e32 v0, v181, v111
	v_mul_f32_e32 v0, 0xbfb8aa3b, v0
	v_exp_f32_e32 v0, v0
	s_nop 0
	v_add_f32_e32 v0, 1.0, v0
	v_rcp_f32_e32 v0, v0
	s_nop 0
	v_mul_f32_e32 v0, 0xbf1b4598, v0
	v_mul_f32_e32 v0, 0x3fb8aa3b, v0
	v_exp_f32_e32 v111, v0
	v_add_f32_e32 v0, v185, v115
	v_mul_f32_e32 v0, 0xbfb8aa3b, v0
	v_exp_f32_e32 v0, v0
	s_nop 0
	v_add_f32_e32 v0, 1.0, v0
	v_rcp_f32_e32 v115, v0
	v_add_f32_e32 v0, v182, v112
	v_mul_f32_e32 v0, 0xbfb8aa3b, v0
	v_exp_f32_e32 v0, v0
	v_pk_add_f32 v[122:123], v[114:115], -1.0 op_sel_hi:[1,0]
	v_pk_mul_f32 v[114:115], v[124:125], v[114:115]
	v_pk_fma_f32 v[54:55], v[54:55], v[122:123], 1.0 op_sel_hi:[1,1,0]
	v_add_f32_e32 v0, 1.0, v0
	v_rcp_f32_e32 v0, v0
	v_pk_mul_f32 v[50:51], v[50:51], v[54:55]
	v_mul_f32_e32 v0, 0xbf1b4598, v0
	v_mul_f32_e32 v0, 0x3fb8aa3b, v0
	v_exp_f32_e32 v112, v0
	v_add_f32_e32 v0, v186, v116
	v_mul_f32_e32 v0, 0xbfb8aa3b, v0
	v_exp_f32_e32 v0, v0
	v_cvt_pk_bf16_f32 v50, v50, v51
	v_add_f32_e32 v0, 1.0, v0
	v_rcp_f32_e32 v54, v0
	v_add_f32_e32 v0, v183, v113
	v_mul_f32_e32 v0, 0xbfb8aa3b, v0
	v_exp_f32_e32 v0, v0
	s_nop 0
	v_add_f32_e32 v0, 1.0, v0
	v_rcp_f32_e32 v0, v0
	s_nop 0
	v_mul_f32_e32 v0, 0xbf1b4598, v0
	v_mul_f32_e32 v0, 0x3fb8aa3b, v0
	v_exp_f32_e32 v113, v0
	v_add_f32_e32 v0, v187, v117
	v_mul_f32_e32 v0, 0xbfb8aa3b, v0
	v_exp_f32_e32 v0, v0
	s_nop 0
	v_add_f32_e32 v0, 1.0, v0
	v_rcp_f32_e32 v55, v0
	s_nop 0
	v_pk_mul_f32 v[116:117], v[128:129], v[54:55]
	v_pk_add_f32 v[54:55], v[54:55], -1.0 op_sel_hi:[1,0]
	global_store_dwordx4 v[120:121], v[110:113], off offset:1024 sc0 sc1
	global_store_dwordx4 v[130:131], v[114:117], off offset:1024 sc0 sc1
	v_pk_fma_f32 v[54:55], v[56:57], v[54:55], 1.0 op_sel_hi:[1,1,0]
	s_nop 0
	v_pk_mul_f32 v[52:53], v[52:53], v[54:55]
	s_nop 0
	v_cvt_pk_bf16_f32 v51, v52, v53
	global_store_dwordx2 v[118:119], v[50:51], off offset:512 sc0 sc1
	s_cbranch_vccnz .LBB0_936
	s_barrier
	s_waitcnt vmcnt(0)
	v_readlane_b32 s2, v251, 40
	v_readlane_b32 s3, v251, 41
	s_barrier
	s_and_saveexec_b64 s[26:27], s[2:3]
	s_cbranch_execz .LBB0_531
	s_mov_b64 s[34:35], exec
	v_mbcnt_lo_u32_b32 v0, s34, 0
	s_waitcnt vmcnt(0)
	s_waitcnt vmcnt(0)
	v_mbcnt_hi_u32_b32 v0, s35, v0
	v_cmp_eq_u32_e32 vcc, 0, v0
	s_and_b64 s[42:43], exec, vcc
	s_mov_b64 exec, s[42:43]
	s_cbranch_execz .LBB0_531
	s_addk_i32 s31, 0xff00
	s_ashr_i32 s2, s31, 31
	v_readlane_b32 s3, v249, 36
	s_xor_b32 s2, s2, s3
	s_abs_i32 s3, s31
	v_readlane_b32 s4, v249, 37
	s_mul_hi_u32 s31, s3, s4
	s_mul_i32 s33, s31, s37
	s_sub_i32 s3, s3, s33
	s_add_i32 s33, s31, 1
	s_sub_i32 s42, s3, s37
	s_cmp_ge_u32 s3, s37
	s_cselect_b32 s31, s33, s31
	s_cselect_b32 s3, s42, s3
	s_add_i32 s33, s31, 1
	s_cmp_ge_u32 s3, s37
	s_cselect_b32 s3, s33, s31
	s_xor_b32 s3, s3, s2
	s_sub_i32 s2, s3, s2
	s_lshl_b32 s42, s2, 6
	s_ashr_i32 s43, s42, 31
	s_lshl_b64 s[42:43], s[42:43], 2
	v_readlane_b32 s2, v250, 56
	s_add_u32 s42, s2, s42
	v_readlane_b32 s2, v250, 57
	s_addc_u32 s43, s2, s43
	s_bcnt1_i32_b64 s2, s[34:35]
	v_mov_b32_e32 v0, s2
	global_atomic_add v1, v0, s[42:43]
	s_branch .LBB0_531
